# P5: K(i+2)/V(i+1) LDS staging writes moved from the end of the step to its top (their buffers are idle during the step); on top of stack6
# baseline (speedup 1.0000x reference)
.LBB0_1802:
	s_add_i32 s2, s83, 3
	s_add_i32 s94, s83, 2
	s_min_i32 s2, s2, s97
	s_min_i32 s3, s94, s97
	s_mul_i32 s2, s2, 0xf8000
	s_mul_i32 s3, s3, 0xf8000
	v_add_u32_e32 v2, s2, v216
	s_waitcnt vmcnt(0)
	ds_write_b128 v231, v[146:149]
	ds_write_b128 v231, v[150:153] offset:27648
	v_add_u32_e32 v8, s3, v216
	global_load_dwordx4 v[4:7], v2, s[84:85]
	s_nop 0
	global_load_dwordx4 v[8:11], v8, s[84:85] offset:128
	s_add_i32 s2, s83, 1
	s_lshl_b32 s95, 1, s2
	v_and_b32_e32 v12, s95, v155
	v_cmp_ne_u32_e64 s[72:73], 0, v12
	s_andn2_b64 vcc, exec, s[0:1]
	s_mov_b64 s[0:1], -1
	v_cndmask_b32_e64 v130, v232, v20, s[72:73]
	v_mov_b32_e32 v131, v130
	v_mov_b32_e32 v132, v130
	v_mov_b32_e32 v133, v130
	v_mov_b32_e32 v134, v130
	v_mov_b32_e32 v135, v130
	v_mov_b32_e32 v136, v130
	v_mov_b32_e32 v137, v130
	v_mov_b32_e32 v138, v130
	v_mov_b32_e32 v139, v130
	v_mov_b32_e32 v140, v130
	v_mov_b32_e32 v141, v130
	v_mov_b32_e32 v142, v130
	v_mov_b32_e32 v143, v130
	v_mov_b32_e32 v144, v130
	v_mov_b32_e32 v145, v130
	s_cbranch_vccz .LBB0_1804
	ds_read_b128 v[12:15], v233 offset:9216
	s_mov_b64 s[0:1], 0
	s_waitcnt lgkmcnt(0)
	v_mfma_f32_32x32x16_bf16 v[66:81], v[12:15], v[206:209], v[130:145]
	ds_read_b128 v[12:15], v233 offset:13824
	s_waitcnt lgkmcnt(0)
	v_mfma_f32_32x32x16_bf16 v[82:97], v[12:15], v[206:209], v[130:145]
	ds_read_b128 v[12:15], v233 offset:9248
	s_waitcnt lgkmcnt(0)
	v_mfma_f32_32x32x16_bf16 v[66:81], v[12:15], v[202:205], v[66:81]
	ds_read_b128 v[12:15], v233 offset:13856
	s_waitcnt lgkmcnt(0)
	v_mfma_f32_32x32x16_bf16 v[82:97], v[12:15], v[202:205], v[82:97]
	ds_read_b128 v[12:15], v233 offset:9280
	s_waitcnt lgkmcnt(0)
	v_mfma_f32_32x32x16_bf16 v[66:81], v[12:15], v[198:201], v[66:81]
	ds_read_b128 v[12:15], v233 offset:13888
	s_waitcnt lgkmcnt(0)
	v_mfma_f32_32x32x16_bf16 v[82:97], v[12:15], v[198:201], v[82:97]
	ds_read_b128 v[12:15], v233 offset:9312
	s_waitcnt lgkmcnt(0)
	v_mfma_f32_32x32x16_bf16 v[66:81], v[12:15], v[194:197], v[66:81]
	ds_read_b128 v[12:15], v233 offset:13920
	s_waitcnt lgkmcnt(0)
	v_mfma_f32_32x32x16_bf16 v[82:97], v[12:15], v[194:197], v[82:97]

.LBB0_1807:
	s_cmp_lg_u64 s[72:73], 0
	s_waitcnt lgkmcnt(0)
	s_barrier
	s_cselect_b64 s[0:1], -1, 0
	s_cmp_eq_u64 s[72:73], 0
	v_lshl_add_u64 v[12:13], s[84:85], 0, v[2:3]
	s_cselect_b64 s[86:87], -1, 0
	s_cmp_gt_i32 s94, s97
	s_cbranch_scc1 .LBB0_1814
	s_waitcnt vmcnt(0)
	ds_write_b128 v231, v[4:7] offset:9216
	ds_write_b128 v231, v[8:11] offset:18432
	s_add_i32 s0, s83, 4
	s_min_i32 s0, s0, s97
	s_mul_i32 s0, s0, 0xf8000
	v_add_u32_e32 v2, s0, v216
	global_load_dwordx4 v[146:149], v2, s[84:85]
	global_load_dwordx4 v[150:153], v[12:13], off offset:128
	s_and_b32 s72, s94, 30
	s_cmp_eq_u32 s72, 0
	s_cselect_b64 vcc, -1, 0
	s_cmp_eq_u32 s83, 30
	s_cselect_b64 s[0:1], -1, 0
	s_cmp_eq_u32 s83, 62
	s_cselect_b64 s[2:3], -1, 0
	v_cndmask_b32_e64 v2, v213, v212, s[2:3]
	v_cndmask_b32_e64 v2, v2, v211, s[0:1]
	v_cndmask_b32_e32 v155, v155, v2, vcc
	v_lshrrev_b32_e32 v2, s72, v155
	v_and_b32_e32 v2, 1, v2
	v_cmp_eq_u32_e32 vcc, 1, v2
	v_bfe_u32 v12, v155, s72, 1
	v_cmp_ne_u32_e64 s[72:73], 0, v12
	v_cndmask_b32_e32 v130, v232, v20, vcc
	v_mov_b32_e32 v131, v130
	v_mov_b32_e32 v132, v130
	v_mov_b32_e32 v133, v130
	v_mov_b32_e32 v134, v130
	v_mov_b32_e32 v135, v130
	v_mov_b32_e32 v136, v130
	v_mov_b32_e32 v137, v130
	v_mov_b32_e32 v138, v130
	v_mov_b32_e32 v139, v130
	v_mov_b32_e32 v140, v130
	v_mov_b32_e32 v141, v130
	v_mov_b32_e32 v142, v130
	v_mov_b32_e32 v143, v130
	v_mov_b32_e32 v144, v130
	v_mov_b32_e32 v145, v130
	s_mov_b64 s[0:1], -1
	s_and_b64 vcc, exec, s[86:87]
	s_cbranch_vccz .LBB0_1810
	ds_read_b128 v[12:15], v233
	s_mov_b64 s[0:1], 0
	s_waitcnt lgkmcnt(0)
	v_mfma_f32_32x32x16_bf16 v[98:113], v[12:15], v[206:209], v[130:145]
	ds_read_b128 v[12:15], v233 offset:4608
	s_waitcnt lgkmcnt(0)
	v_mfma_f32_32x32x16_bf16 v[114:129], v[12:15], v[206:209], v[130:145]
	ds_read_b128 v[12:15], v233 offset:32
	s_waitcnt lgkmcnt(0)
	v_mfma_f32_32x32x16_bf16 v[98:113], v[12:15], v[202:205], v[98:113]
	ds_read_b128 v[12:15], v233 offset:4640
	s_waitcnt lgkmcnt(0)
	v_mfma_f32_32x32x16_bf16 v[114:129], v[12:15], v[202:205], v[114:129]
	ds_read_b128 v[12:15], v233 offset:64
	s_waitcnt lgkmcnt(0)
	v_mfma_f32_32x32x16_bf16 v[98:113], v[12:15], v[198:201], v[98:113]
	ds_read_b128 v[12:15], v233 offset:4672
	s_waitcnt lgkmcnt(0)
	v_mfma_f32_32x32x16_bf16 v[114:129], v[12:15], v[198:201], v[114:129]
	ds_read_b128 v[12:15], v233 offset:96
	s_waitcnt lgkmcnt(0)
	v_mfma_f32_32x32x16_bf16 v[98:113], v[12:15], v[194:197], v[98:113]
	ds_read_b128 v[12:15], v233 offset:4704
	s_waitcnt lgkmcnt(0)
	v_mfma_f32_32x32x16_bf16 v[114:129], v[12:15], v[194:197], v[114:129]

.LBB0_1813:
	s_waitcnt lgkmcnt(0)
	s_barrier
	s_cmp_lg_u64 s[72:73], 0
	s_cselect_b64 s[0:1], -1, 0

.LBB0_1818:
	s_nop 0
	v_readlane_b32 s94, v247, 42
	v_readlane_b32 s95, v247, 43
	s_branch .LBB0_1820
